# v9: v6 plus rope-projection epilogues load the next row group's cos/sin one group ahead into spare registers and wait with a counted vmcnt (no store-ack stalls)
# speedup vs baseline: 1.0149x; 1.0008x over previous
; __device__ __forceinline__ unsigned cvt_pk_bf16(float lo, float hi) { unsigned r; asm volatile("v_cvt_pk_bf16_f32 %0, %1, %2" : "=v"(r) : "v"(lo), "v"(hi)); return r; }
;     __device__ __forceinline__ void operator()(const f32x4 (&acc)[2][2][4][2], const Unit& u, int wr, int wc, int fr, int fq) const {
;     ...
;             for (int m = 0; m < 4; ++m) { const int rl = wr * 64 + fr + ai * HALF + m * 16, row = u.pm * BM + rl; const float rsc = tab[rl];
;                 const f32x4 c = *(const f32x4*)(cs + (size_t)(row & 4095) * half + d0), s = *(const f32x4*)(sn + (size_t)(row & 4095) * half + d0);
;                 bf16_t* rowp = O + (size_t)row * ldc + gcol;
; #pragma unroll
;                 for (int bj = 0; bj < 2; ++bj) { const f32x4 x1 = acc[ai][bj][m][0] * rsc, x2 = acc[ai][bj][m][1] * rsc;
;                     const f32x4 y1 = x1 * c - x2 * s, y2 = x2 * c + x1 * s;
;                     u32x2 w1, w2; w1.x = cvt_pk_bf16(y1[0], y1[1]); w1.y = cvt_pk_bf16(y1[2], y1[3]); w2.x = cvt_pk_bf16(y2[0], y2[1]); w2.y = cvt_pk_bf16(y2[2], y2[3]);
;                     *(u32x2*)(rowp + bj * HALF) = w1; *(u32x2*)(rowp + bj * HALF + half) = w2; } }
.LBB0_487:
	v_lshrrev_b32_e32 v0, 2, v143
	v_and_b32_e32 v0, 28, v0
	s_waitcnt lgkmcnt(0)
	v_add_u32_e32 v146, s90, v0
	v_or_b32_e32 v0, s77, v142
	v_add_u32_e32 v151, s23, v0
	s_lshl_b32 s3, s3, 8
	v_lshl_add_u32 v152, v0, 2, v243
	v_lshlrev_b32_e32 v0, 7, v151
	s_or_b32 s3, s3, s44
	v_and_b32_e32 v0, 0x7e780, v0
	v_add_u32_e32 v144, s3, v146
	v_lshl_add_u64 v[142:143], s[14:15], 0, v[0:1]
	v_lshlrev_b32_e32 v146, 2, v146
	v_mov_b32_e32 v147, v1
	v_lshl_add_u64 v[142:143], v[142:143], 0, v[146:147]
	global_load_dwordx4 v[154:157], v[142:143], off
	v_lshl_add_u64 v[142:143], s[16:17], 0, v[0:1]
	v_lshl_add_u64 v[142:143], v[142:143], 0, v[146:147]
	global_load_dwordx4 v[158:161], v[142:143], off
	ds_read_b32 v162, v152
	v_ashrrev_i32_e32 v145, 31, v144
	v_mov_b64_e32 v[142:143], s[12:13]
	v_mad_i64_i32 v[164:165], s[30:31], v151, s75, v[142:143]
	s_waitcnt lgkmcnt(0)
	v_pk_mul_f32 v[122:123], v[122:123], v[162:163] op_sel_hi:[1,0]
	v_pk_mul_f32 v[126:127], v[126:127], v[162:163] op_sel_hi:[1,0]
	v_pk_mul_f32 v[124:125], v[124:125], v[162:163] op_sel_hi:[1,0]
	v_lshlrev_b64 v[144:145], 1, v[144:145]
	v_pk_mul_f32 v[128:129], v[128:129], v[162:163] op_sel_hi:[1,0]
	v_lshl_add_u64 v[164:165], v[164:165], 0, v[144:145]
	v_pk_mul_f32 v[116:117], v[116:117], v[162:163] op_sel_hi:[1,0]
	v_pk_mul_f32 v[120:121], v[120:121], v[162:163] op_sel_hi:[1,0]
	v_pk_mul_f32 v[114:115], v[114:115], v[162:163] op_sel_hi:[1,0]
	v_pk_mul_f32 v[118:119], v[118:119], v[162:163] op_sel_hi:[1,0]
	s_andn2_b64 vcc, exec, s[6:7]
	s_waitcnt vmcnt(0)
	v_add_u32_e32 v170, 16, v151
	v_lshlrev_b32_e32 v170, 7, v170
	v_and_b32_e32 v170, 0x7ff80, v170
	v_mov_b32_e32 v171, 0
	v_lshl_add_u64 v[180:181], s[14:15], 0, v[170:171]
	v_lshl_add_u64 v[184:185], s[16:17], 0, v[170:171]
	v_lshl_add_u64 v[180:181], v[180:181], 0, v[146:147]
	v_lshl_add_u64 v[184:185], v[184:185], 0, v[146:147]
	global_load_dwordx4 v[180:183], v[180:181], off
	global_load_dwordx4 v[184:187], v[184:185], off
	v_pk_mul_f32 v[168:169], v[158:159], v[122:123]
	v_pk_mul_f32 v[122:123], v[154:155], v[122:123]
	v_pk_mul_f32 v[166:167], v[160:161], v[124:125]
	v_pk_mul_f32 v[124:125], v[156:157], v[124:125]
	v_pk_fma_f32 v[122:123], v[158:159], v[126:127], v[122:123]
	v_pk_fma_f32 v[166:167], v[156:157], v[128:129], v[166:167] neg_lo:[0,0,1] neg_hi:[0,0,1]
	v_pk_fma_f32 v[168:169], v[154:155], v[126:127], v[168:169] neg_lo:[0,0,1] neg_hi:[0,0,1]
	v_pk_fma_f32 v[124:125], v[160:161], v[128:129], v[124:125]
	v_cvt_pk_bf16_f32 v126, v168, v169
	v_cvt_pk_bf16_f32 v127, v166, v167
	v_cvt_pk_bf16_f32 v122, v122, v123
	s_nop 0
	v_cvt_pk_bf16_f32 v123, v124, v125
	global_store_dwordx2 v[164:165], v[126:127], off
	global_store_dwordx2 v[164:165], v[122:123], off offset:64
	v_pk_mul_f32 v[122:123], v[160:161], v[116:117]
	v_pk_mul_f32 v[124:125], v[158:159], v[114:115]
	v_pk_fma_f32 v[122:123], v[156:157], v[120:121], v[122:123] neg_lo:[0,0,1] neg_hi:[0,0,1]
	v_pk_mul_f32 v[114:115], v[154:155], v[114:115]
	v_pk_fma_f32 v[124:125], v[154:155], v[118:119], v[124:125] neg_lo:[0,0,1] neg_hi:[0,0,1]
	v_pk_fma_f32 v[114:115], v[158:159], v[118:119], v[114:115]
	v_cvt_pk_bf16_f32 v118, v124, v125
	v_cvt_pk_bf16_f32 v119, v122, v123
	v_add_u32_e32 v123, 16, v151
	v_pk_mul_f32 v[116:117], v[156:157], v[116:117]
	v_lshlrev_b32_e32 v0, 7, v123
	v_pk_fma_f32 v[116:117], v[160:161], v[120:121], v[116:117]
	v_cvt_pk_bf16_f32 v114, v114, v115
	v_and_b32_e32 v0, 0x7ef80, v0
	v_cvt_pk_bf16_f32 v115, v116, v117
	global_store_dwordx2 v[164:165], v[118:119], off offset:256
	global_store_dwordx2 v[164:165], v[114:115], off offset:320
	v_lshl_add_u64 v[114:115], s[14:15], 0, v[0:1]
	v_lshl_add_u64 v[118:119], s[16:17], 0, v[0:1]
	v_lshl_add_u64 v[114:115], v[114:115], 0, v[146:147]
	v_lshl_add_u64 v[118:119], v[118:119], 0, v[146:147]
	ds_read_b32 v122, v152 offset:64
	v_mad_i64_i32 v[124:125], s[30:31], v123, s75, v[142:143]
	v_lshl_add_u64 v[124:125], v[124:125], 0, v[144:145]
	s_waitcnt lgkmcnt(0)
	v_pk_mul_f32 v[106:107], v[106:107], v[122:123] op_sel_hi:[1,0]
	v_pk_mul_f32 v[110:111], v[110:111], v[122:123] op_sel_hi:[1,0]
	v_pk_mul_f32 v[108:109], v[108:109], v[122:123] op_sel_hi:[1,0]
	v_pk_mul_f32 v[112:113], v[112:113], v[122:123] op_sel_hi:[1,0]
	v_pk_mul_f32 v[100:101], v[100:101], v[122:123] op_sel_hi:[1,0]
	v_pk_mul_f32 v[104:105], v[104:105], v[122:123] op_sel_hi:[1,0]
	v_pk_mul_f32 v[98:99], v[98:99], v[122:123] op_sel_hi:[1,0]
	v_pk_mul_f32 v[102:103], v[102:103], v[122:123] op_sel_hi:[1,0]
	s_waitcnt vmcnt(4)
; __device__ __forceinline__ unsigned cvt_pk_bf16(float lo, float hi) { unsigned r; asm volatile("v_cvt_pk_bf16_f32 %0, %1, %2" : "=v"(r) : "v"(lo), "v"(hi)); return r; }
;     __device__ __forceinline__ void operator()(const f32x4 (&acc)[2][2][4][2], const Unit& u, int wr, int wc, int fr, int fq) const {
;     ...
;             for (int m = 0; m < 4; ++m) { const int rl = wr * 64 + fr + ai * HALF + m * 16, row = u.pm * BM + rl; const float rsc = tab[rl];
;                 const f32x4 c = *(const f32x4*)(cs + (size_t)(row & 4095) * half + d0), s = *(const f32x4*)(sn + (size_t)(row & 4095) * half + d0);
;                 bf16_t* rowp = O + (size_t)row * ldc + gcol;
; #pragma unroll
;                 for (int bj = 0; bj < 2; ++bj) { const f32x4 x1 = acc[ai][bj][m][0] * rsc, x2 = acc[ai][bj][m][1] * rsc;
;                     const f32x4 y1 = x1 * c - x2 * s, y2 = x2 * c + x1 * s;
;                     u32x2 w1, w2; w1.x = cvt_pk_bf16(y1[0], y1[1]); w1.y = cvt_pk_bf16(y1[2], y1[3]); w2.x = cvt_pk_bf16(y2[0], y2[1]); w2.y = cvt_pk_bf16(y2[2], y2[3]);
;                     *(u32x2*)(rowp + bj * HALF) = w1; *(u32x2*)(rowp + bj * HALF + half) = w2; } }
	v_add_u32_e32 v170, 32, v151
	v_lshlrev_b32_e32 v170, 7, v170
	v_and_b32_e32 v170, 0x7ff80, v170
	v_mov_b32_e32 v171, 0
	v_lshl_add_u64 v[172:173], s[14:15], 0, v[170:171]
	v_lshl_add_u64 v[176:177], s[16:17], 0, v[170:171]
	v_lshl_add_u64 v[172:173], v[172:173], 0, v[146:147]
	v_lshl_add_u64 v[176:177], v[176:177], 0, v[146:147]
	global_load_dwordx4 v[172:175], v[172:173], off
	global_load_dwordx4 v[176:179], v[176:177], off
	v_pk_mul_f32 v[128:129], v[184:185], v[106:107]
	v_pk_mul_f32 v[106:107], v[180:181], v[106:107]
	v_pk_mul_f32 v[126:127], v[186:187], v[108:109]
	v_pk_mul_f32 v[108:109], v[182:183], v[108:109]
	v_pk_fma_f32 v[106:107], v[184:185], v[110:111], v[106:107]
	v_pk_fma_f32 v[126:127], v[182:183], v[112:113], v[126:127] neg_lo:[0,0,1] neg_hi:[0,0,1]
	v_pk_fma_f32 v[128:129], v[180:181], v[110:111], v[128:129] neg_lo:[0,0,1] neg_hi:[0,0,1]
	v_pk_fma_f32 v[108:109], v[186:187], v[112:113], v[108:109]
	v_cvt_pk_bf16_f32 v110, v128, v129
	v_cvt_pk_bf16_f32 v111, v126, v127
	v_cvt_pk_bf16_f32 v106, v106, v107
	s_nop 0
	v_cvt_pk_bf16_f32 v107, v108, v109
	global_store_dwordx2 v[124:125], v[110:111], off
	global_store_dwordx2 v[124:125], v[106:107], off offset:64
	v_pk_mul_f32 v[106:107], v[186:187], v[100:101]
	v_pk_mul_f32 v[108:109], v[184:185], v[98:99]
	v_pk_fma_f32 v[106:107], v[182:183], v[104:105], v[106:107] neg_lo:[0,0,1] neg_hi:[0,0,1]
	v_pk_mul_f32 v[98:99], v[180:181], v[98:99]
	v_pk_fma_f32 v[108:109], v[180:181], v[102:103], v[108:109] neg_lo:[0,0,1] neg_hi:[0,0,1]
	v_pk_fma_f32 v[98:99], v[184:185], v[102:103], v[98:99]
	v_cvt_pk_bf16_f32 v102, v108, v109
	v_cvt_pk_bf16_f32 v103, v106, v107
	v_add_u32_e32 v107, 32, v151
	v_pk_mul_f32 v[100:101], v[182:183], v[100:101]
	v_lshlrev_b32_e32 v0, 7, v107
	v_pk_fma_f32 v[100:101], v[186:187], v[104:105], v[100:101]
	v_cvt_pk_bf16_f32 v98, v98, v99
	v_and_b32_e32 v0, 0x7f780, v0
	v_cvt_pk_bf16_f32 v99, v100, v101
	global_store_dwordx2 v[124:125], v[102:103], off offset:256
	global_store_dwordx2 v[124:125], v[98:99], off offset:320
	v_lshl_add_u64 v[98:99], s[14:15], 0, v[0:1]
	v_lshl_add_u64 v[102:103], s[16:17], 0, v[0:1]
	v_lshl_add_u64 v[98:99], v[98:99], 0, v[146:147]
	v_lshl_add_u64 v[102:103], v[102:103], 0, v[146:147]
	ds_read_b32 v106, v152 offset:128
	v_mad_i64_i32 v[108:109], s[30:31], v107, s75, v[142:143]
	v_lshl_add_u64 v[108:109], v[108:109], 0, v[144:145]
	s_waitcnt lgkmcnt(0)
	v_pk_mul_f32 v[90:91], v[90:91], v[106:107] op_sel_hi:[1,0]
	v_pk_mul_f32 v[94:95], v[94:95], v[106:107] op_sel_hi:[1,0]
	v_pk_mul_f32 v[92:93], v[92:93], v[106:107] op_sel_hi:[1,0]
	v_pk_mul_f32 v[96:97], v[96:97], v[106:107] op_sel_hi:[1,0]
	v_pk_mul_f32 v[84:85], v[84:85], v[106:107] op_sel_hi:[1,0]
	v_pk_mul_f32 v[88:89], v[88:89], v[106:107] op_sel_hi:[1,0]
	v_pk_mul_f32 v[82:83], v[82:83], v[106:107] op_sel_hi:[1,0]
	v_pk_mul_f32 v[86:87], v[86:87], v[106:107] op_sel_hi:[1,0]
	s_waitcnt vmcnt(4)
	v_add_u32_e32 v170, 48, v151
	v_lshlrev_b32_e32 v170, 7, v170
	v_and_b32_e32 v170, 0x7ff80, v170
	v_mov_b32_e32 v171, 0
	v_lshl_add_u64 v[180:181], s[14:15], 0, v[170:171]
	v_lshl_add_u64 v[184:185], s[16:17], 0, v[170:171]
	v_lshl_add_u64 v[180:181], v[180:181], 0, v[146:147]
	v_lshl_add_u64 v[184:185], v[184:185], 0, v[146:147]
	global_load_dwordx4 v[180:183], v[180:181], off
	global_load_dwordx4 v[184:187], v[184:185], off
	v_pk_mul_f32 v[112:113], v[176:177], v[90:91]
	v_pk_mul_f32 v[90:91], v[172:173], v[90:91]
	v_pk_mul_f32 v[110:111], v[178:179], v[92:93]
	v_pk_mul_f32 v[92:93], v[174:175], v[92:93]
	v_pk_fma_f32 v[90:91], v[176:177], v[94:95], v[90:91]
	v_pk_fma_f32 v[110:111], v[174:175], v[96:97], v[110:111] neg_lo:[0,0,1] neg_hi:[0,0,1]
	v_pk_fma_f32 v[112:113], v[172:173], v[94:95], v[112:113] neg_lo:[0,0,1] neg_hi:[0,0,1]
	v_pk_fma_f32 v[92:93], v[178:179], v[96:97], v[92:93]
	v_cvt_pk_bf16_f32 v94, v112, v113
	v_cvt_pk_bf16_f32 v95, v110, v111
	v_cvt_pk_bf16_f32 v90, v90, v91
	s_nop 0
	v_cvt_pk_bf16_f32 v91, v92, v93
	global_store_dwordx2 v[108:109], v[94:95], off
	global_store_dwordx2 v[108:109], v[90:91], off offset:64
	v_pk_mul_f32 v[90:91], v[178:179], v[84:85]
	v_pk_mul_f32 v[92:93], v[176:177], v[82:83]
	v_pk_fma_f32 v[90:91], v[174:175], v[88:89], v[90:91] neg_lo:[0,0,1] neg_hi:[0,0,1]
	v_pk_mul_f32 v[82:83], v[172:173], v[82:83]
	v_pk_fma_f32 v[92:93], v[172:173], v[86:87], v[92:93] neg_lo:[0,0,1] neg_hi:[0,0,1]
	v_pk_fma_f32 v[82:83], v[176:177], v[86:87], v[82:83]
	v_cvt_pk_bf16_f32 v86, v92, v93
	v_cvt_pk_bf16_f32 v87, v90, v91
	v_add_u32_e32 v91, 48, v151
	v_pk_mul_f32 v[84:85], v[174:175], v[84:85]
	v_lshlrev_b32_e32 v0, 7, v91
	v_pk_fma_f32 v[84:85], v[178:179], v[88:89], v[84:85]
	v_cvt_pk_bf16_f32 v82, v82, v83
	v_and_b32_e32 v0, 0x7ff80, v0
	v_cvt_pk_bf16_f32 v83, v84, v85
	global_store_dwordx2 v[108:109], v[86:87], off offset:256
	global_store_dwordx2 v[108:109], v[82:83], off offset:320
	v_lshl_add_u64 v[82:83], s[14:15], 0, v[0:1]
	v_lshl_add_u64 v[86:87], s[16:17], 0, v[0:1]
	v_lshl_add_u64 v[82:83], v[82:83], 0, v[146:147]
	v_lshl_add_u64 v[86:87], v[86:87], 0, v[146:147]
	ds_read_b32 v90, v152 offset:192
	v_mad_i64_i32 v[92:93], s[30:31], v91, s75, v[142:143]
	v_lshl_add_u64 v[92:93], v[92:93], 0, v[144:145]
	s_waitcnt lgkmcnt(0)
	v_pk_mul_f32 v[74:75], v[74:75], v[90:91] op_sel_hi:[1,0]
	v_pk_mul_f32 v[78:79], v[78:79], v[90:91] op_sel_hi:[1,0]
	v_pk_mul_f32 v[76:77], v[76:77], v[90:91] op_sel_hi:[1,0]
	v_pk_mul_f32 v[80:81], v[80:81], v[90:91] op_sel_hi:[1,0]
	v_pk_mul_f32 v[68:69], v[68:69], v[90:91] op_sel_hi:[1,0]
	v_pk_mul_f32 v[72:73], v[72:73], v[90:91] op_sel_hi:[1,0]
	v_pk_mul_f32 v[66:67], v[66:67], v[90:91] op_sel_hi:[1,0]
	v_pk_mul_f32 v[70:71], v[70:71], v[90:91] op_sel_hi:[1,0]
	s_waitcnt vmcnt(4)
; __device__ __forceinline__ unsigned cvt_pk_bf16(float lo, float hi) { unsigned r; asm volatile("v_cvt_pk_bf16_f32 %0, %1, %2" : "=v"(r) : "v"(lo), "v"(hi)); return r; }
;     __device__ __forceinline__ void operator()(const f32x4 (&acc)[2][2][4][2], const Unit& u, int wr, int wc, int fr, int fq) const {
;     ...
;             for (int m = 0; m < 4; ++m) { const int rl = wr * 64 + fr + ai * HALF + m * 16, row = u.pm * BM + rl; const float rsc = tab[rl];
;                 const f32x4 c = *(const f32x4*)(cs + (size_t)(row & 4095) * half + d0), s = *(const f32x4*)(sn + (size_t)(row & 4095) * half + d0);
;                 bf16_t* rowp = O + (size_t)row * ldc + gcol;
; #pragma unroll
;                 for (int bj = 0; bj < 2; ++bj) { const f32x4 x1 = acc[ai][bj][m][0] * rsc, x2 = acc[ai][bj][m][1] * rsc;
;                     const f32x4 y1 = x1 * c - x2 * s, y2 = x2 * c + x1 * s;
;                     u32x2 w1, w2; w1.x = cvt_pk_bf16(y1[0], y1[1]); w1.y = cvt_pk_bf16(y1[2], y1[3]); w2.x = cvt_pk_bf16(y2[0], y2[1]); w2.y = cvt_pk_bf16(y2[2], y2[3]);
;                     *(u32x2*)(rowp + bj * HALF) = w1; *(u32x2*)(rowp + bj * HALF + half) = w2; } }
	v_add_u32_e32 v170, 128, v151
	v_lshlrev_b32_e32 v170, 7, v170
	v_and_b32_e32 v170, 0x7ff80, v170
	v_mov_b32_e32 v171, 0
	v_lshl_add_u64 v[172:173], s[14:15], 0, v[170:171]
	v_lshl_add_u64 v[176:177], s[16:17], 0, v[170:171]
	v_lshl_add_u64 v[172:173], v[172:173], 0, v[146:147]
	v_lshl_add_u64 v[176:177], v[176:177], 0, v[146:147]
	global_load_dwordx4 v[172:175], v[172:173], off
	global_load_dwordx4 v[176:179], v[176:177], off
	v_pk_mul_f32 v[96:97], v[184:185], v[74:75]
	v_pk_mul_f32 v[74:75], v[180:181], v[74:75]
	v_pk_mul_f32 v[94:95], v[186:187], v[76:77]
	v_pk_mul_f32 v[76:77], v[182:183], v[76:77]
	v_pk_fma_f32 v[74:75], v[184:185], v[78:79], v[74:75]
	v_pk_fma_f32 v[94:95], v[182:183], v[80:81], v[94:95] neg_lo:[0,0,1] neg_hi:[0,0,1]
	v_pk_fma_f32 v[96:97], v[180:181], v[78:79], v[96:97] neg_lo:[0,0,1] neg_hi:[0,0,1]
	v_pk_fma_f32 v[76:77], v[186:187], v[80:81], v[76:77]
	v_cvt_pk_bf16_f32 v78, v96, v97
	v_cvt_pk_bf16_f32 v79, v94, v95
	v_cvt_pk_bf16_f32 v74, v74, v75
	s_nop 0
	v_cvt_pk_bf16_f32 v75, v76, v77
	global_store_dwordx2 v[92:93], v[78:79], off
	global_store_dwordx2 v[92:93], v[74:75], off offset:64
	v_pk_mul_f32 v[74:75], v[186:187], v[68:69]
	v_pk_mul_f32 v[76:77], v[184:185], v[66:67]
	v_pk_fma_f32 v[74:75], v[182:183], v[72:73], v[74:75] neg_lo:[0,0,1] neg_hi:[0,0,1]
	v_pk_mul_f32 v[66:67], v[180:181], v[66:67]
	v_pk_fma_f32 v[76:77], v[180:181], v[70:71], v[76:77] neg_lo:[0,0,1] neg_hi:[0,0,1]
	v_pk_fma_f32 v[66:67], v[184:185], v[70:71], v[66:67]
	v_cvt_pk_bf16_f32 v70, v76, v77
	v_cvt_pk_bf16_f32 v71, v74, v75
	v_add_u32_e32 v75, 0x80, v151
	v_pk_mul_f32 v[68:69], v[182:183], v[68:69]
	v_lshlrev_b32_e32 v0, 7, v75
	v_pk_fma_f32 v[68:69], v[186:187], v[72:73], v[68:69]
	v_cvt_pk_bf16_f32 v66, v66, v67
	v_and_b32_e32 v0, 0x7e780, v0
	v_cvt_pk_bf16_f32 v67, v68, v69
	global_store_dwordx2 v[92:93], v[70:71], off offset:256
	global_store_dwordx2 v[92:93], v[66:67], off offset:320
	v_lshl_add_u64 v[66:67], s[14:15], 0, v[0:1]
	v_lshl_add_u64 v[70:71], s[16:17], 0, v[0:1]
	v_lshl_add_u64 v[66:67], v[66:67], 0, v[146:147]
	v_lshl_add_u64 v[70:71], v[70:71], 0, v[146:147]
	ds_read_b32 v74, v152 offset:512
	v_mad_i64_i32 v[76:77], s[30:31], v75, s75, v[142:143]
	v_lshl_add_u64 v[76:77], v[76:77], 0, v[144:145]
	s_waitcnt lgkmcnt(0)
	v_pk_mul_f32 v[58:59], v[58:59], v[74:75] op_sel_hi:[1,0]
	v_pk_mul_f32 v[62:63], v[62:63], v[74:75] op_sel_hi:[1,0]
	v_pk_mul_f32 v[60:61], v[60:61], v[74:75] op_sel_hi:[1,0]
	v_pk_mul_f32 v[64:65], v[64:65], v[74:75] op_sel_hi:[1,0]
	v_pk_mul_f32 v[52:53], v[52:53], v[74:75] op_sel_hi:[1,0]
	v_pk_mul_f32 v[56:57], v[56:57], v[74:75] op_sel_hi:[1,0]
	v_pk_mul_f32 v[50:51], v[50:51], v[74:75] op_sel_hi:[1,0]
	v_pk_mul_f32 v[54:55], v[54:55], v[74:75] op_sel_hi:[1,0]
	s_waitcnt vmcnt(4)
	v_add_u32_e32 v170, 144, v151
	v_lshlrev_b32_e32 v170, 7, v170
	v_and_b32_e32 v170, 0x7ff80, v170
	v_mov_b32_e32 v171, 0
	v_lshl_add_u64 v[180:181], s[14:15], 0, v[170:171]
	v_lshl_add_u64 v[184:185], s[16:17], 0, v[170:171]
	v_lshl_add_u64 v[180:181], v[180:181], 0, v[146:147]
	v_lshl_add_u64 v[184:185], v[184:185], 0, v[146:147]
	global_load_dwordx4 v[180:183], v[180:181], off
	global_load_dwordx4 v[184:187], v[184:185], off
	v_pk_mul_f32 v[80:81], v[176:177], v[58:59]
	v_pk_mul_f32 v[58:59], v[172:173], v[58:59]
	v_pk_mul_f32 v[78:79], v[178:179], v[60:61]
	v_pk_mul_f32 v[60:61], v[174:175], v[60:61]
	v_pk_fma_f32 v[58:59], v[176:177], v[62:63], v[58:59]
	v_pk_fma_f32 v[78:79], v[174:175], v[64:65], v[78:79] neg_lo:[0,0,1] neg_hi:[0,0,1]
	v_pk_fma_f32 v[80:81], v[172:173], v[62:63], v[80:81] neg_lo:[0,0,1] neg_hi:[0,0,1]
	v_pk_fma_f32 v[60:61], v[178:179], v[64:65], v[60:61]
	v_cvt_pk_bf16_f32 v62, v80, v81
	v_cvt_pk_bf16_f32 v63, v78, v79
	v_cvt_pk_bf16_f32 v58, v58, v59
	s_nop 0
	v_cvt_pk_bf16_f32 v59, v60, v61
	global_store_dwordx2 v[76:77], v[62:63], off
	global_store_dwordx2 v[76:77], v[58:59], off offset:64
	v_pk_mul_f32 v[58:59], v[178:179], v[52:53]
	v_pk_mul_f32 v[60:61], v[176:177], v[50:51]
	v_pk_fma_f32 v[58:59], v[174:175], v[56:57], v[58:59] neg_lo:[0,0,1] neg_hi:[0,0,1]
	v_pk_mul_f32 v[50:51], v[172:173], v[50:51]
	v_pk_fma_f32 v[60:61], v[172:173], v[54:55], v[60:61] neg_lo:[0,0,1] neg_hi:[0,0,1]
	v_pk_fma_f32 v[50:51], v[176:177], v[54:55], v[50:51]
	v_cvt_pk_bf16_f32 v54, v60, v61
	v_cvt_pk_bf16_f32 v55, v58, v59
	v_add_u32_e32 v59, 0x90, v151
	v_pk_mul_f32 v[52:53], v[174:175], v[52:53]
	v_lshlrev_b32_e32 v0, 7, v59
	v_pk_fma_f32 v[52:53], v[178:179], v[56:57], v[52:53]
	v_cvt_pk_bf16_f32 v50, v50, v51
	v_and_b32_e32 v0, 0x7ef80, v0
	v_cvt_pk_bf16_f32 v51, v52, v53
	global_store_dwordx2 v[76:77], v[54:55], off offset:256
	global_store_dwordx2 v[76:77], v[50:51], off offset:320
	v_lshl_add_u64 v[50:51], s[14:15], 0, v[0:1]
	v_lshl_add_u64 v[54:55], s[16:17], 0, v[0:1]
	v_lshl_add_u64 v[50:51], v[50:51], 0, v[146:147]
	v_lshl_add_u64 v[54:55], v[54:55], 0, v[146:147]
	ds_read_b32 v58, v152 offset:576
	v_mad_i64_i32 v[60:61], s[30:31], v59, s75, v[142:143]
	v_lshl_add_u64 v[60:61], v[60:61], 0, v[144:145]
	s_waitcnt lgkmcnt(0)
	v_pk_mul_f32 v[42:43], v[42:43], v[58:59] op_sel_hi:[1,0]
	v_pk_mul_f32 v[46:47], v[46:47], v[58:59] op_sel_hi:[1,0]
	v_pk_mul_f32 v[44:45], v[44:45], v[58:59] op_sel_hi:[1,0]
	v_pk_mul_f32 v[48:49], v[48:49], v[58:59] op_sel_hi:[1,0]
	v_pk_mul_f32 v[36:37], v[36:37], v[58:59] op_sel_hi:[1,0]
	v_pk_mul_f32 v[40:41], v[40:41], v[58:59] op_sel_hi:[1,0]
	v_pk_mul_f32 v[34:35], v[34:35], v[58:59] op_sel_hi:[1,0]
	v_pk_mul_f32 v[38:39], v[38:39], v[58:59] op_sel_hi:[1,0]
	s_waitcnt vmcnt(4)
; __device__ __forceinline__ unsigned cvt_pk_bf16(float lo, float hi) { unsigned r; asm volatile("v_cvt_pk_bf16_f32 %0, %1, %2" : "=v"(r) : "v"(lo), "v"(hi)); return r; }
;     __device__ __forceinline__ void operator()(const f32x4 (&acc)[2][2][4][2], const Unit& u, int wr, int wc, int fr, int fq) const {
;     ...
;             for (int m = 0; m < 4; ++m) { const int rl = wr * 64 + fr + ai * HALF + m * 16, row = u.pm * BM + rl; const float rsc = tab[rl];
;                 const f32x4 c = *(const f32x4*)(cs + (size_t)(row & 4095) * half + d0), s = *(const f32x4*)(sn + (size_t)(row & 4095) * half + d0);
;                 bf16_t* rowp = O + (size_t)row * ldc + gcol;
; #pragma unroll
;                 for (int bj = 0; bj < 2; ++bj) { const f32x4 x1 = acc[ai][bj][m][0] * rsc, x2 = acc[ai][bj][m][1] * rsc;
;                     const f32x4 y1 = x1 * c - x2 * s, y2 = x2 * c + x1 * s;
;                     u32x2 w1, w2; w1.x = cvt_pk_bf16(y1[0], y1[1]); w1.y = cvt_pk_bf16(y1[2], y1[3]); w2.x = cvt_pk_bf16(y2[0], y2[1]); w2.y = cvt_pk_bf16(y2[2], y2[3]);
;                     *(u32x2*)(rowp + bj * HALF) = w1; *(u32x2*)(rowp + bj * HALF + half) = w2; } }
	v_add_u32_e32 v170, 160, v151
	v_lshlrev_b32_e32 v170, 7, v170
	v_and_b32_e32 v170, 0x7ff80, v170
	v_mov_b32_e32 v171, 0
	v_lshl_add_u64 v[172:173], s[14:15], 0, v[170:171]
	v_lshl_add_u64 v[176:177], s[16:17], 0, v[170:171]
	v_lshl_add_u64 v[172:173], v[172:173], 0, v[146:147]
	v_lshl_add_u64 v[176:177], v[176:177], 0, v[146:147]
	global_load_dwordx4 v[172:175], v[172:173], off
	global_load_dwordx4 v[176:179], v[176:177], off
	v_pk_mul_f32 v[64:65], v[184:185], v[42:43]
	v_pk_mul_f32 v[42:43], v[180:181], v[42:43]
	v_pk_mul_f32 v[62:63], v[186:187], v[44:45]
	v_pk_mul_f32 v[44:45], v[182:183], v[44:45]
	v_pk_fma_f32 v[42:43], v[184:185], v[46:47], v[42:43]
	v_pk_fma_f32 v[62:63], v[182:183], v[48:49], v[62:63] neg_lo:[0,0,1] neg_hi:[0,0,1]
	v_pk_fma_f32 v[64:65], v[180:181], v[46:47], v[64:65] neg_lo:[0,0,1] neg_hi:[0,0,1]
	v_pk_fma_f32 v[44:45], v[186:187], v[48:49], v[44:45]
	v_cvt_pk_bf16_f32 v46, v64, v65
	v_cvt_pk_bf16_f32 v47, v62, v63
	v_cvt_pk_bf16_f32 v42, v42, v43
	s_nop 0
	v_cvt_pk_bf16_f32 v43, v44, v45
	global_store_dwordx2 v[60:61], v[46:47], off
	global_store_dwordx2 v[60:61], v[42:43], off offset:64
	v_pk_mul_f32 v[42:43], v[186:187], v[36:37]
	v_pk_mul_f32 v[44:45], v[184:185], v[34:35]
	v_pk_fma_f32 v[42:43], v[182:183], v[40:41], v[42:43] neg_lo:[0,0,1] neg_hi:[0,0,1]
	v_pk_mul_f32 v[34:35], v[180:181], v[34:35]
	v_pk_fma_f32 v[44:45], v[180:181], v[38:39], v[44:45] neg_lo:[0,0,1] neg_hi:[0,0,1]
	v_pk_fma_f32 v[34:35], v[184:185], v[38:39], v[34:35]
	v_cvt_pk_bf16_f32 v38, v44, v45
	v_cvt_pk_bf16_f32 v39, v42, v43
	v_add_u32_e32 v43, 0xa0, v151
	v_pk_mul_f32 v[36:37], v[182:183], v[36:37]
	v_lshlrev_b32_e32 v0, 7, v43
	v_pk_fma_f32 v[36:37], v[186:187], v[40:41], v[36:37]
	v_cvt_pk_bf16_f32 v34, v34, v35
	v_and_b32_e32 v0, 0x7f780, v0
	v_cvt_pk_bf16_f32 v35, v36, v37
	global_store_dwordx2 v[60:61], v[38:39], off offset:256
	global_store_dwordx2 v[60:61], v[34:35], off offset:320
	v_lshl_add_u64 v[34:35], s[14:15], 0, v[0:1]
	v_lshl_add_u64 v[38:39], s[16:17], 0, v[0:1]
	v_lshl_add_u64 v[34:35], v[34:35], 0, v[146:147]
	v_lshl_add_u64 v[38:39], v[38:39], 0, v[146:147]
	ds_read_b32 v42, v152 offset:640
	v_mad_i64_i32 v[44:45], s[30:31], v43, s75, v[142:143]
	v_lshl_add_u64 v[44:45], v[44:45], 0, v[144:145]
	s_waitcnt lgkmcnt(0)
	v_pk_mul_f32 v[26:27], v[26:27], v[42:43] op_sel_hi:[1,0]
	v_pk_mul_f32 v[30:31], v[30:31], v[42:43] op_sel_hi:[1,0]
	v_pk_mul_f32 v[28:29], v[28:29], v[42:43] op_sel_hi:[1,0]
	v_pk_mul_f32 v[32:33], v[32:33], v[42:43] op_sel_hi:[1,0]
	v_pk_mul_f32 v[20:21], v[20:21], v[42:43] op_sel_hi:[1,0]
	v_pk_mul_f32 v[24:25], v[24:25], v[42:43] op_sel_hi:[1,0]
	v_pk_mul_f32 v[18:19], v[18:19], v[42:43] op_sel_hi:[1,0]
	v_pk_mul_f32 v[22:23], v[22:23], v[42:43] op_sel_hi:[1,0]
	s_waitcnt vmcnt(4)
	v_add_u32_e32 v170, 176, v151
	v_lshlrev_b32_e32 v170, 7, v170
	v_and_b32_e32 v170, 0x7ff80, v170
	v_mov_b32_e32 v171, 0
	v_lshl_add_u64 v[180:181], s[14:15], 0, v[170:171]
	v_lshl_add_u64 v[184:185], s[16:17], 0, v[170:171]
	v_lshl_add_u64 v[180:181], v[180:181], 0, v[146:147]
	v_lshl_add_u64 v[184:185], v[184:185], 0, v[146:147]
	global_load_dwordx4 v[180:183], v[180:181], off
	global_load_dwordx4 v[184:187], v[184:185], off
	v_pk_mul_f32 v[48:49], v[176:177], v[26:27]
	v_pk_mul_f32 v[26:27], v[172:173], v[26:27]
	v_pk_mul_f32 v[46:47], v[178:179], v[28:29]
	v_pk_mul_f32 v[28:29], v[174:175], v[28:29]
	v_pk_fma_f32 v[26:27], v[176:177], v[30:31], v[26:27]
	v_pk_fma_f32 v[46:47], v[174:175], v[32:33], v[46:47] neg_lo:[0,0,1] neg_hi:[0,0,1]
	v_pk_fma_f32 v[48:49], v[172:173], v[30:31], v[48:49] neg_lo:[0,0,1] neg_hi:[0,0,1]
	v_pk_fma_f32 v[28:29], v[178:179], v[32:33], v[28:29]
	v_cvt_pk_bf16_f32 v30, v48, v49
	v_cvt_pk_bf16_f32 v31, v46, v47
	v_cvt_pk_bf16_f32 v26, v26, v27
	s_nop 0
	v_cvt_pk_bf16_f32 v27, v28, v29
	global_store_dwordx2 v[44:45], v[30:31], off
	global_store_dwordx2 v[44:45], v[26:27], off offset:64
	v_pk_mul_f32 v[26:27], v[178:179], v[20:21]
	v_pk_mul_f32 v[28:29], v[176:177], v[18:19]
	v_pk_fma_f32 v[26:27], v[174:175], v[24:25], v[26:27] neg_lo:[0,0,1] neg_hi:[0,0,1]
	v_pk_mul_f32 v[18:19], v[172:173], v[18:19]
	v_pk_fma_f32 v[28:29], v[172:173], v[22:23], v[28:29] neg_lo:[0,0,1] neg_hi:[0,0,1]
	v_pk_fma_f32 v[18:19], v[176:177], v[22:23], v[18:19]
	v_cvt_pk_bf16_f32 v22, v28, v29
	v_cvt_pk_bf16_f32 v23, v26, v27
	v_add_u32_e32 v27, 0xb0, v151
	v_pk_mul_f32 v[20:21], v[174:175], v[20:21]
	v_lshlrev_b32_e32 v0, 7, v27
	v_pk_fma_f32 v[20:21], v[178:179], v[24:25], v[20:21]
	v_cvt_pk_bf16_f32 v18, v18, v19
	v_and_b32_e32 v0, 0x7ff80, v0
	v_cvt_pk_bf16_f32 v19, v20, v21
	global_store_dwordx2 v[44:45], v[22:23], off offset:256
	global_store_dwordx2 v[44:45], v[18:19], off offset:320
	v_lshl_add_u64 v[18:19], s[14:15], 0, v[0:1]
	v_lshl_add_u64 v[22:23], s[16:17], 0, v[0:1]
	v_lshl_add_u64 v[18:19], v[18:19], 0, v[146:147]
	v_lshl_add_u64 v[22:23], v[22:23], 0, v[146:147]
	ds_read_b32 v26, v152 offset:704
	v_mad_i64_i32 v[28:29], s[30:31], v27, s75, v[142:143]
	v_lshl_add_u64 v[28:29], v[28:29], 0, v[144:145]
	s_waitcnt lgkmcnt(0)
	v_pk_mul_f32 v[10:11], v[10:11], v[26:27] op_sel_hi:[1,0]
	v_pk_mul_f32 v[14:15], v[14:15], v[26:27] op_sel_hi:[1,0]
	v_pk_mul_f32 v[12:13], v[12:13], v[26:27] op_sel_hi:[1,0]
	v_pk_mul_f32 v[16:17], v[16:17], v[26:27] op_sel_hi:[1,0]
	v_pk_mul_f32 v[4:5], v[4:5], v[26:27] op_sel_hi:[1,0]
	v_pk_mul_f32 v[2:3], v[2:3], v[26:27] op_sel_hi:[1,0]
	v_pk_mul_f32 v[8:9], v[8:9], v[26:27] op_sel_hi:[1,0]
	v_pk_mul_f32 v[6:7], v[6:7], v[26:27] op_sel_hi:[1,0]
	s_mov_b64 s[30:31], -1
	s_waitcnt vmcnt(4)
	v_pk_mul_f32 v[32:33], v[184:185], v[10:11]
	v_pk_mul_f32 v[10:11], v[180:181], v[10:11]
	v_pk_mul_f32 v[30:31], v[186:187], v[12:13]
	v_pk_mul_f32 v[12:13], v[182:183], v[12:13]
	v_pk_fma_f32 v[10:11], v[184:185], v[14:15], v[10:11]
	v_pk_fma_f32 v[30:31], v[182:183], v[16:17], v[30:31] neg_lo:[0,0,1] neg_hi:[0,0,1]
	v_pk_fma_f32 v[32:33], v[180:181], v[14:15], v[32:33] neg_lo:[0,0,1] neg_hi:[0,0,1]
	v_pk_fma_f32 v[12:13], v[186:187], v[16:17], v[12:13]
	v_cvt_pk_bf16_f32 v14, v32, v33
	v_cvt_pk_bf16_f32 v15, v30, v31
	v_cvt_pk_bf16_f32 v10, v10, v11
	s_nop 0
	v_cvt_pk_bf16_f32 v11, v12, v13
	global_store_dwordx2 v[28:29], v[14:15], off
	global_store_dwordx2 v[28:29], v[10:11], off offset:64
	v_pk_mul_f32 v[10:11], v[186:187], v[4:5]
	v_pk_mul_f32 v[12:13], v[184:185], v[2:3]
	v_pk_mul_f32 v[2:3], v[180:181], v[2:3]
	v_pk_fma_f32 v[10:11], v[182:183], v[8:9], v[10:11] neg_lo:[0,0,1] neg_hi:[0,0,1]
	v_pk_fma_f32 v[12:13], v[180:181], v[6:7], v[12:13] neg_lo:[0,0,1] neg_hi:[0,0,1]
	v_pk_mul_f32 v[4:5], v[182:183], v[4:5]
	v_pk_fma_f32 v[2:3], v[184:185], v[6:7], v[2:3]
	v_cvt_pk_bf16_f32 v6, v12, v13
	v_cvt_pk_bf16_f32 v7, v10, v11
	v_pk_fma_f32 v[4:5], v[186:187], v[8:9], v[4:5]
	v_cvt_pk_bf16_f32 v2, v2, v3
	s_nop 0
	v_cvt_pk_bf16_f32 v3, v4, v5
	global_store_dwordx2 v[28:29], v[6:7], off offset:256
	global_store_dwordx2 v[28:29], v[2:3], off offset:320
	s_cbranch_vccnz .LBB0_470
; #define PG8_BAR __builtin_amdgcn_s_barrier()
; template <class Epi, class Sched, bool ALIGN_EPI = false, bool SP2 = false>
; __device__ __forceinline__ void gemm_phase(PG8_LAS unsigned char* lds, const Gemm g, const Sched& S, const Epi& E, const int wid) {
;     ...
;         if (!has_next) break;
; #pragma unroll
;         for (int a = 0; a < 2; ++a)
; #pragma unroll
;             for (int b = 0; b < 2; ++b)
; #pragma unroll
;                 for (int m = 0; m < 4; ++m)
; #pragma unroll
;                     for (int n = 0; n < 2; ++n) acc[a][b][m][n] = (f32x4){zf_, zf_, zf_, zf_};
;         cur = nxt; cA = nA; cB = nB; ++ui;
;         if constexpr (ALIGN_EPI) { if (wr == 1) PG8_BAR; }
	s_andn2_b64 vcc, exec, s[10:11]
	s_cbranch_vccnz .LBB0_469
	s_barrier
	s_branch .LBB0_469

; __device__ __forceinline__ unsigned cvt_pk_bf16(float lo, float hi) { unsigned r; asm volatile("v_cvt_pk_bf16_f32 %0, %1, %2" : "=v"(r) : "v"(lo), "v"(hi)); return r; }
;     __device__ __forceinline__ void operator()(const f32x4 (&acc)[2][2][4][2], const Unit& u, int wr, int wc, int fr, int fq) const {
;     ...
;             for (int m = 0; m < 4; ++m) { const int rl = wr * 64 + fr + ai * HALF + m * 16, row = u.pm * BM + rl; const float rsc = tab[rl];
;                 const f32x4 c = *(const f32x4*)(cs + (size_t)(row & 4095) * half + d0), s = *(const f32x4*)(sn + (size_t)(row & 4095) * half + d0);
;                 bf16_t* rowp = O + (size_t)row * ldc + gcol;
; #pragma unroll
;                 for (int bj = 0; bj < 2; ++bj) { const f32x4 x1 = acc[ai][bj][m][0] * rsc, x2 = acc[ai][bj][m][1] * rsc;
;                     const f32x4 y1 = x1 * c - x2 * s, y2 = x2 * c + x1 * s;
;                     u32x2 w1, w2; w1.x = cvt_pk_bf16(y1[0], y1[1]); w1.y = cvt_pk_bf16(y1[2], y1[3]); w2.x = cvt_pk_bf16(y2[0], y2[1]); w2.y = cvt_pk_bf16(y2[2], y2[3]);
;                     *(u32x2*)(rowp + bj * HALF) = w1; *(u32x2*)(rowp + bj * HALF + half) = w2; } }
.LBB0_509:
	v_lshrrev_b32_e32 v0, 2, v143
	v_and_b32_e32 v0, 28, v0
	s_waitcnt lgkmcnt(0)
	v_add_u32_e32 v146, s90, v0
	v_or_b32_e32 v0, s77, v142
	v_add_u32_e32 v151, s23, v0
	v_lshl_add_u32 v152, v0, 2, v243
	v_lshlrev_b32_e32 v0, 8, v151
	v_and_b32_e32 v0, 0xfcf00, v0
	v_lshl_or_b32 v144, s3, 8, v146
	v_lshl_add_u64 v[142:143], s[14:15], 0, v[0:1]
	v_lshlrev_b32_e32 v146, 2, v146
	v_mov_b32_e32 v147, v1
	v_lshl_add_u64 v[142:143], v[142:143], 0, v[146:147]
	global_load_dwordx4 v[154:157], v[142:143], off
	v_lshl_add_u64 v[142:143], s[16:17], 0, v[0:1]
	v_lshl_add_u64 v[142:143], v[142:143], 0, v[146:147]
	global_load_dwordx4 v[158:161], v[142:143], off
	ds_read_b32 v162, v152
	v_ashrrev_i32_e32 v145, 31, v144
	v_mov_b64_e32 v[142:143], s[12:13]
	v_mad_i64_i32 v[164:165], s[30:31], v151, s75, v[142:143]
	s_waitcnt lgkmcnt(0)
	v_pk_mul_f32 v[122:123], v[122:123], v[162:163] op_sel_hi:[1,0]
	v_pk_mul_f32 v[126:127], v[126:127], v[162:163] op_sel_hi:[1,0]
	v_pk_mul_f32 v[124:125], v[124:125], v[162:163] op_sel_hi:[1,0]
	v_lshlrev_b64 v[144:145], 1, v[144:145]
	v_pk_mul_f32 v[128:129], v[128:129], v[162:163] op_sel_hi:[1,0]
	v_lshl_add_u64 v[164:165], v[164:165], 0, v[144:145]
	v_pk_mul_f32 v[116:117], v[116:117], v[162:163] op_sel_hi:[1,0]
	v_pk_mul_f32 v[120:121], v[120:121], v[162:163] op_sel_hi:[1,0]
	v_pk_mul_f32 v[114:115], v[114:115], v[162:163] op_sel_hi:[1,0]
	v_pk_mul_f32 v[118:119], v[118:119], v[162:163] op_sel_hi:[1,0]
	s_andn2_b64 vcc, exec, s[6:7]
	s_waitcnt vmcnt(0)
	v_add_u32_e32 v170, 16, v151
	v_lshlrev_b32_e32 v170, 8, v170
	v_and_b32_e32 v170, 0xfff00, v170
	v_mov_b32_e32 v171, 0
	v_lshl_add_u64 v[180:181], s[14:15], 0, v[170:171]
	v_lshl_add_u64 v[184:185], s[16:17], 0, v[170:171]
	v_lshl_add_u64 v[180:181], v[180:181], 0, v[146:147]
	v_lshl_add_u64 v[184:185], v[184:185], 0, v[146:147]
	global_load_dwordx4 v[180:183], v[180:181], off
	global_load_dwordx4 v[184:187], v[184:185], off
	v_pk_mul_f32 v[168:169], v[158:159], v[122:123]
	v_pk_mul_f32 v[122:123], v[154:155], v[122:123]
	v_pk_mul_f32 v[166:167], v[160:161], v[124:125]
	v_pk_mul_f32 v[124:125], v[156:157], v[124:125]
	v_pk_fma_f32 v[122:123], v[158:159], v[126:127], v[122:123]
	v_pk_fma_f32 v[166:167], v[156:157], v[128:129], v[166:167] neg_lo:[0,0,1] neg_hi:[0,0,1]
	v_pk_fma_f32 v[168:169], v[154:155], v[126:127], v[168:169] neg_lo:[0,0,1] neg_hi:[0,0,1]
	v_pk_fma_f32 v[124:125], v[160:161], v[128:129], v[124:125]
	v_cvt_pk_bf16_f32 v126, v168, v169
	v_cvt_pk_bf16_f32 v127, v166, v167
	v_cvt_pk_bf16_f32 v122, v122, v123
	s_nop 0
	v_cvt_pk_bf16_f32 v123, v124, v125
	global_store_dwordx2 v[164:165], v[126:127], off
	global_store_dwordx2 v[164:165], v[122:123], off offset:128
	v_pk_mul_f32 v[122:123], v[160:161], v[116:117]
	v_pk_mul_f32 v[124:125], v[158:159], v[114:115]
	v_pk_fma_f32 v[122:123], v[156:157], v[120:121], v[122:123] neg_lo:[0,0,1] neg_hi:[0,0,1]
	v_pk_mul_f32 v[114:115], v[154:155], v[114:115]
	v_pk_fma_f32 v[124:125], v[154:155], v[118:119], v[124:125] neg_lo:[0,0,1] neg_hi:[0,0,1]
	v_pk_fma_f32 v[114:115], v[158:159], v[118:119], v[114:115]
	v_cvt_pk_bf16_f32 v118, v124, v125
	v_cvt_pk_bf16_f32 v119, v122, v123
	v_add_u32_e32 v123, 16, v151
	v_pk_mul_f32 v[116:117], v[156:157], v[116:117]
	v_lshlrev_b32_e32 v0, 8, v123
	v_pk_fma_f32 v[116:117], v[160:161], v[120:121], v[116:117]
	v_cvt_pk_bf16_f32 v114, v114, v115
	v_and_b32_e32 v0, 0xfdf00, v0
	v_cvt_pk_bf16_f32 v115, v116, v117
	global_store_dwordx2 v[164:165], v[118:119], off offset:256
	global_store_dwordx2 v[164:165], v[114:115], off offset:384
	v_lshl_add_u64 v[114:115], s[14:15], 0, v[0:1]
	v_lshl_add_u64 v[118:119], s[16:17], 0, v[0:1]
	v_lshl_add_u64 v[114:115], v[114:115], 0, v[146:147]
	v_lshl_add_u64 v[118:119], v[118:119], 0, v[146:147]
	ds_read_b32 v122, v152 offset:64
	v_mad_i64_i32 v[124:125], s[30:31], v123, s75, v[142:143]
	v_lshl_add_u64 v[124:125], v[124:125], 0, v[144:145]
	s_waitcnt lgkmcnt(0)
	v_pk_mul_f32 v[106:107], v[106:107], v[122:123] op_sel_hi:[1,0]
	v_pk_mul_f32 v[110:111], v[110:111], v[122:123] op_sel_hi:[1,0]
	v_pk_mul_f32 v[108:109], v[108:109], v[122:123] op_sel_hi:[1,0]
	v_pk_mul_f32 v[112:113], v[112:113], v[122:123] op_sel_hi:[1,0]
	v_pk_mul_f32 v[100:101], v[100:101], v[122:123] op_sel_hi:[1,0]
	v_pk_mul_f32 v[104:105], v[104:105], v[122:123] op_sel_hi:[1,0]
	v_pk_mul_f32 v[98:99], v[98:99], v[122:123] op_sel_hi:[1,0]
	v_pk_mul_f32 v[102:103], v[102:103], v[122:123] op_sel_hi:[1,0]
	s_waitcnt vmcnt(4)
; __device__ __forceinline__ unsigned cvt_pk_bf16(float lo, float hi) { unsigned r; asm volatile("v_cvt_pk_bf16_f32 %0, %1, %2" : "=v"(r) : "v"(lo), "v"(hi)); return r; }
;     __device__ __forceinline__ void operator()(const f32x4 (&acc)[2][2][4][2], const Unit& u, int wr, int wc, int fr, int fq) const {
;     ...
;             for (int m = 0; m < 4; ++m) { const int rl = wr * 64 + fr + ai * HALF + m * 16, row = u.pm * BM + rl; const float rsc = tab[rl];
;                 const f32x4 c = *(const f32x4*)(cs + (size_t)(row & 4095) * half + d0), s = *(const f32x4*)(sn + (size_t)(row & 4095) * half + d0);
;                 bf16_t* rowp = O + (size_t)row * ldc + gcol;
; #pragma unroll
;                 for (int bj = 0; bj < 2; ++bj) { const f32x4 x1 = acc[ai][bj][m][0] * rsc, x2 = acc[ai][bj][m][1] * rsc;
;                     const f32x4 y1 = x1 * c - x2 * s, y2 = x2 * c + x1 * s;
;                     u32x2 w1, w2; w1.x = cvt_pk_bf16(y1[0], y1[1]); w1.y = cvt_pk_bf16(y1[2], y1[3]); w2.x = cvt_pk_bf16(y2[0], y2[1]); w2.y = cvt_pk_bf16(y2[2], y2[3]);
;                     *(u32x2*)(rowp + bj * HALF) = w1; *(u32x2*)(rowp + bj * HALF + half) = w2; } }
	v_add_u32_e32 v170, 32, v151
	v_lshlrev_b32_e32 v170, 8, v170
	v_and_b32_e32 v170, 0xfff00, v170
	v_mov_b32_e32 v171, 0
	v_lshl_add_u64 v[172:173], s[14:15], 0, v[170:171]
	v_lshl_add_u64 v[176:177], s[16:17], 0, v[170:171]
	v_lshl_add_u64 v[172:173], v[172:173], 0, v[146:147]
	v_lshl_add_u64 v[176:177], v[176:177], 0, v[146:147]
	global_load_dwordx4 v[172:175], v[172:173], off
	global_load_dwordx4 v[176:179], v[176:177], off
	v_pk_mul_f32 v[128:129], v[184:185], v[106:107]
	v_pk_mul_f32 v[106:107], v[180:181], v[106:107]
	v_pk_mul_f32 v[126:127], v[186:187], v[108:109]
	v_pk_mul_f32 v[108:109], v[182:183], v[108:109]
	v_pk_fma_f32 v[106:107], v[184:185], v[110:111], v[106:107]
	v_pk_fma_f32 v[126:127], v[182:183], v[112:113], v[126:127] neg_lo:[0,0,1] neg_hi:[0,0,1]
	v_pk_fma_f32 v[128:129], v[180:181], v[110:111], v[128:129] neg_lo:[0,0,1] neg_hi:[0,0,1]
	v_pk_fma_f32 v[108:109], v[186:187], v[112:113], v[108:109]
	v_cvt_pk_bf16_f32 v110, v128, v129
	v_cvt_pk_bf16_f32 v111, v126, v127
	v_cvt_pk_bf16_f32 v106, v106, v107
	s_nop 0
	v_cvt_pk_bf16_f32 v107, v108, v109
	global_store_dwordx2 v[124:125], v[110:111], off
	global_store_dwordx2 v[124:125], v[106:107], off offset:128
	v_pk_mul_f32 v[106:107], v[186:187], v[100:101]
	v_pk_mul_f32 v[108:109], v[184:185], v[98:99]
	v_pk_fma_f32 v[106:107], v[182:183], v[104:105], v[106:107] neg_lo:[0,0,1] neg_hi:[0,0,1]
	v_pk_mul_f32 v[98:99], v[180:181], v[98:99]
	v_pk_fma_f32 v[108:109], v[180:181], v[102:103], v[108:109] neg_lo:[0,0,1] neg_hi:[0,0,1]
	v_pk_fma_f32 v[98:99], v[184:185], v[102:103], v[98:99]
	v_cvt_pk_bf16_f32 v102, v108, v109
	v_cvt_pk_bf16_f32 v103, v106, v107
	v_add_u32_e32 v107, 32, v151
	v_pk_mul_f32 v[100:101], v[182:183], v[100:101]
	v_lshlrev_b32_e32 v0, 8, v107
	v_pk_fma_f32 v[100:101], v[186:187], v[104:105], v[100:101]
	v_cvt_pk_bf16_f32 v98, v98, v99
	v_and_b32_e32 v0, 0xfef00, v0
	v_cvt_pk_bf16_f32 v99, v100, v101
	global_store_dwordx2 v[124:125], v[102:103], off offset:256
	global_store_dwordx2 v[124:125], v[98:99], off offset:384
	v_lshl_add_u64 v[98:99], s[14:15], 0, v[0:1]
	v_lshl_add_u64 v[102:103], s[16:17], 0, v[0:1]
	v_lshl_add_u64 v[98:99], v[98:99], 0, v[146:147]
	v_lshl_add_u64 v[102:103], v[102:103], 0, v[146:147]
	ds_read_b32 v106, v152 offset:128
	v_mad_i64_i32 v[108:109], s[30:31], v107, s75, v[142:143]
	v_lshl_add_u64 v[108:109], v[108:109], 0, v[144:145]
	s_waitcnt lgkmcnt(0)
	v_pk_mul_f32 v[90:91], v[90:91], v[106:107] op_sel_hi:[1,0]
	v_pk_mul_f32 v[94:95], v[94:95], v[106:107] op_sel_hi:[1,0]
	v_pk_mul_f32 v[92:93], v[92:93], v[106:107] op_sel_hi:[1,0]
	v_pk_mul_f32 v[96:97], v[96:97], v[106:107] op_sel_hi:[1,0]
	v_pk_mul_f32 v[84:85], v[84:85], v[106:107] op_sel_hi:[1,0]
	v_pk_mul_f32 v[88:89], v[88:89], v[106:107] op_sel_hi:[1,0]
	v_pk_mul_f32 v[82:83], v[82:83], v[106:107] op_sel_hi:[1,0]
	v_pk_mul_f32 v[86:87], v[86:87], v[106:107] op_sel_hi:[1,0]
	s_waitcnt vmcnt(4)
	v_add_u32_e32 v170, 48, v151
	v_lshlrev_b32_e32 v170, 8, v170
	v_and_b32_e32 v170, 0xfff00, v170
	v_mov_b32_e32 v171, 0
	v_lshl_add_u64 v[180:181], s[14:15], 0, v[170:171]
	v_lshl_add_u64 v[184:185], s[16:17], 0, v[170:171]
	v_lshl_add_u64 v[180:181], v[180:181], 0, v[146:147]
	v_lshl_add_u64 v[184:185], v[184:185], 0, v[146:147]
	global_load_dwordx4 v[180:183], v[180:181], off
	global_load_dwordx4 v[184:187], v[184:185], off
	v_pk_mul_f32 v[112:113], v[176:177], v[90:91]
	v_pk_mul_f32 v[90:91], v[172:173], v[90:91]
	v_pk_mul_f32 v[110:111], v[178:179], v[92:93]
	v_pk_mul_f32 v[92:93], v[174:175], v[92:93]
	v_pk_fma_f32 v[90:91], v[176:177], v[94:95], v[90:91]
	v_pk_fma_f32 v[110:111], v[174:175], v[96:97], v[110:111] neg_lo:[0,0,1] neg_hi:[0,0,1]
	v_pk_fma_f32 v[112:113], v[172:173], v[94:95], v[112:113] neg_lo:[0,0,1] neg_hi:[0,0,1]
	v_pk_fma_f32 v[92:93], v[178:179], v[96:97], v[92:93]
	v_cvt_pk_bf16_f32 v94, v112, v113
	v_cvt_pk_bf16_f32 v95, v110, v111
	v_cvt_pk_bf16_f32 v90, v90, v91
	s_nop 0
	v_cvt_pk_bf16_f32 v91, v92, v93
	global_store_dwordx2 v[108:109], v[94:95], off
	global_store_dwordx2 v[108:109], v[90:91], off offset:128
	v_pk_mul_f32 v[90:91], v[178:179], v[84:85]
	v_pk_mul_f32 v[92:93], v[176:177], v[82:83]
	v_pk_fma_f32 v[90:91], v[174:175], v[88:89], v[90:91] neg_lo:[0,0,1] neg_hi:[0,0,1]
	v_pk_mul_f32 v[82:83], v[172:173], v[82:83]
	v_pk_fma_f32 v[92:93], v[172:173], v[86:87], v[92:93] neg_lo:[0,0,1] neg_hi:[0,0,1]
	v_pk_fma_f32 v[82:83], v[176:177], v[86:87], v[82:83]
	v_cvt_pk_bf16_f32 v86, v92, v93
	v_cvt_pk_bf16_f32 v87, v90, v91
	v_add_u32_e32 v91, 48, v151
	v_pk_mul_f32 v[84:85], v[174:175], v[84:85]
	v_lshlrev_b32_e32 v0, 8, v91
	v_pk_fma_f32 v[84:85], v[178:179], v[88:89], v[84:85]
	v_cvt_pk_bf16_f32 v82, v82, v83
	v_and_b32_e32 v0, 0xfff00, v0
	v_cvt_pk_bf16_f32 v83, v84, v85
	global_store_dwordx2 v[108:109], v[86:87], off offset:256
	global_store_dwordx2 v[108:109], v[82:83], off offset:384
	v_lshl_add_u64 v[82:83], s[14:15], 0, v[0:1]
	v_lshl_add_u64 v[86:87], s[16:17], 0, v[0:1]
	v_lshl_add_u64 v[82:83], v[82:83], 0, v[146:147]
	v_lshl_add_u64 v[86:87], v[86:87], 0, v[146:147]
	ds_read_b32 v90, v152 offset:192
	v_mad_i64_i32 v[92:93], s[30:31], v91, s75, v[142:143]
	v_lshl_add_u64 v[92:93], v[92:93], 0, v[144:145]
	s_waitcnt lgkmcnt(0)
	v_pk_mul_f32 v[74:75], v[74:75], v[90:91] op_sel_hi:[1,0]
	v_pk_mul_f32 v[78:79], v[78:79], v[90:91] op_sel_hi:[1,0]
	v_pk_mul_f32 v[76:77], v[76:77], v[90:91] op_sel_hi:[1,0]
	v_pk_mul_f32 v[80:81], v[80:81], v[90:91] op_sel_hi:[1,0]
	v_pk_mul_f32 v[68:69], v[68:69], v[90:91] op_sel_hi:[1,0]
	v_pk_mul_f32 v[72:73], v[72:73], v[90:91] op_sel_hi:[1,0]
	v_pk_mul_f32 v[66:67], v[66:67], v[90:91] op_sel_hi:[1,0]
	v_pk_mul_f32 v[70:71], v[70:71], v[90:91] op_sel_hi:[1,0]
	s_waitcnt vmcnt(4)
; __device__ __forceinline__ unsigned cvt_pk_bf16(float lo, float hi) { unsigned r; asm volatile("v_cvt_pk_bf16_f32 %0, %1, %2" : "=v"(r) : "v"(lo), "v"(hi)); return r; }
;     __device__ __forceinline__ void operator()(const f32x4 (&acc)[2][2][4][2], const Unit& u, int wr, int wc, int fr, int fq) const {
;     ...
;             for (int m = 0; m < 4; ++m) { const int rl = wr * 64 + fr + ai * HALF + m * 16, row = u.pm * BM + rl; const float rsc = tab[rl];
;                 const f32x4 c = *(const f32x4*)(cs + (size_t)(row & 4095) * half + d0), s = *(const f32x4*)(sn + (size_t)(row & 4095) * half + d0);
;                 bf16_t* rowp = O + (size_t)row * ldc + gcol;
; #pragma unroll
;                 for (int bj = 0; bj < 2; ++bj) { const f32x4 x1 = acc[ai][bj][m][0] * rsc, x2 = acc[ai][bj][m][1] * rsc;
;                     const f32x4 y1 = x1 * c - x2 * s, y2 = x2 * c + x1 * s;
;                     u32x2 w1, w2; w1.x = cvt_pk_bf16(y1[0], y1[1]); w1.y = cvt_pk_bf16(y1[2], y1[3]); w2.x = cvt_pk_bf16(y2[0], y2[1]); w2.y = cvt_pk_bf16(y2[2], y2[3]);
;                     *(u32x2*)(rowp + bj * HALF) = w1; *(u32x2*)(rowp + bj * HALF + half) = w2; } }
	v_add_u32_e32 v170, 128, v151
	v_lshlrev_b32_e32 v170, 8, v170
	v_and_b32_e32 v170, 0xfff00, v170
	v_mov_b32_e32 v171, 0
	v_lshl_add_u64 v[172:173], s[14:15], 0, v[170:171]
	v_lshl_add_u64 v[176:177], s[16:17], 0, v[170:171]
	v_lshl_add_u64 v[172:173], v[172:173], 0, v[146:147]
	v_lshl_add_u64 v[176:177], v[176:177], 0, v[146:147]
	global_load_dwordx4 v[172:175], v[172:173], off
	global_load_dwordx4 v[176:179], v[176:177], off
	v_pk_mul_f32 v[96:97], v[184:185], v[74:75]
	v_pk_mul_f32 v[74:75], v[180:181], v[74:75]
	v_pk_mul_f32 v[94:95], v[186:187], v[76:77]
	v_pk_mul_f32 v[76:77], v[182:183], v[76:77]
	v_pk_fma_f32 v[74:75], v[184:185], v[78:79], v[74:75]
	v_pk_fma_f32 v[94:95], v[182:183], v[80:81], v[94:95] neg_lo:[0,0,1] neg_hi:[0,0,1]
	v_pk_fma_f32 v[96:97], v[180:181], v[78:79], v[96:97] neg_lo:[0,0,1] neg_hi:[0,0,1]
	v_pk_fma_f32 v[76:77], v[186:187], v[80:81], v[76:77]
	v_cvt_pk_bf16_f32 v78, v96, v97
	v_cvt_pk_bf16_f32 v79, v94, v95
	v_cvt_pk_bf16_f32 v74, v74, v75
	s_nop 0
	v_cvt_pk_bf16_f32 v75, v76, v77
	global_store_dwordx2 v[92:93], v[78:79], off
	global_store_dwordx2 v[92:93], v[74:75], off offset:128
	v_pk_mul_f32 v[74:75], v[186:187], v[68:69]
	v_pk_mul_f32 v[76:77], v[184:185], v[66:67]
	v_pk_fma_f32 v[74:75], v[182:183], v[72:73], v[74:75] neg_lo:[0,0,1] neg_hi:[0,0,1]
	v_pk_mul_f32 v[66:67], v[180:181], v[66:67]
	v_pk_fma_f32 v[76:77], v[180:181], v[70:71], v[76:77] neg_lo:[0,0,1] neg_hi:[0,0,1]
	v_pk_fma_f32 v[66:67], v[184:185], v[70:71], v[66:67]
	v_cvt_pk_bf16_f32 v70, v76, v77
	v_cvt_pk_bf16_f32 v71, v74, v75
	v_add_u32_e32 v75, 0x80, v151
	v_pk_mul_f32 v[68:69], v[182:183], v[68:69]
	v_lshlrev_b32_e32 v0, 8, v75
	v_pk_fma_f32 v[68:69], v[186:187], v[72:73], v[68:69]
	v_cvt_pk_bf16_f32 v66, v66, v67
	v_and_b32_e32 v0, 0xfcf00, v0
	v_cvt_pk_bf16_f32 v67, v68, v69
	global_store_dwordx2 v[92:93], v[70:71], off offset:256
	global_store_dwordx2 v[92:93], v[66:67], off offset:384
	v_lshl_add_u64 v[66:67], s[14:15], 0, v[0:1]
	v_lshl_add_u64 v[70:71], s[16:17], 0, v[0:1]
	v_lshl_add_u64 v[66:67], v[66:67], 0, v[146:147]
	v_lshl_add_u64 v[70:71], v[70:71], 0, v[146:147]
	ds_read_b32 v74, v152 offset:512
	v_mad_i64_i32 v[76:77], s[30:31], v75, s75, v[142:143]
	v_lshl_add_u64 v[76:77], v[76:77], 0, v[144:145]
	s_waitcnt lgkmcnt(0)
	v_pk_mul_f32 v[58:59], v[58:59], v[74:75] op_sel_hi:[1,0]
	v_pk_mul_f32 v[62:63], v[62:63], v[74:75] op_sel_hi:[1,0]
	v_pk_mul_f32 v[60:61], v[60:61], v[74:75] op_sel_hi:[1,0]
	v_pk_mul_f32 v[64:65], v[64:65], v[74:75] op_sel_hi:[1,0]
	v_pk_mul_f32 v[52:53], v[52:53], v[74:75] op_sel_hi:[1,0]
	v_pk_mul_f32 v[56:57], v[56:57], v[74:75] op_sel_hi:[1,0]
	v_pk_mul_f32 v[50:51], v[50:51], v[74:75] op_sel_hi:[1,0]
	v_pk_mul_f32 v[54:55], v[54:55], v[74:75] op_sel_hi:[1,0]
	s_waitcnt vmcnt(4)
	v_add_u32_e32 v170, 144, v151
	v_lshlrev_b32_e32 v170, 8, v170
	v_and_b32_e32 v170, 0xfff00, v170
	v_mov_b32_e32 v171, 0
	v_lshl_add_u64 v[180:181], s[14:15], 0, v[170:171]
	v_lshl_add_u64 v[184:185], s[16:17], 0, v[170:171]
	v_lshl_add_u64 v[180:181], v[180:181], 0, v[146:147]
	v_lshl_add_u64 v[184:185], v[184:185], 0, v[146:147]
	global_load_dwordx4 v[180:183], v[180:181], off
	global_load_dwordx4 v[184:187], v[184:185], off
	v_pk_mul_f32 v[80:81], v[176:177], v[58:59]
	v_pk_mul_f32 v[58:59], v[172:173], v[58:59]
	v_pk_mul_f32 v[78:79], v[178:179], v[60:61]
	v_pk_mul_f32 v[60:61], v[174:175], v[60:61]
	v_pk_fma_f32 v[58:59], v[176:177], v[62:63], v[58:59]
	v_pk_fma_f32 v[78:79], v[174:175], v[64:65], v[78:79] neg_lo:[0,0,1] neg_hi:[0,0,1]
	v_pk_fma_f32 v[80:81], v[172:173], v[62:63], v[80:81] neg_lo:[0,0,1] neg_hi:[0,0,1]
	v_pk_fma_f32 v[60:61], v[178:179], v[64:65], v[60:61]
	v_cvt_pk_bf16_f32 v62, v80, v81
	v_cvt_pk_bf16_f32 v63, v78, v79
	v_cvt_pk_bf16_f32 v58, v58, v59
	s_nop 0
	v_cvt_pk_bf16_f32 v59, v60, v61
	global_store_dwordx2 v[76:77], v[62:63], off
	global_store_dwordx2 v[76:77], v[58:59], off offset:128
	v_pk_mul_f32 v[58:59], v[178:179], v[52:53]
	v_pk_mul_f32 v[60:61], v[176:177], v[50:51]
	v_pk_fma_f32 v[58:59], v[174:175], v[56:57], v[58:59] neg_lo:[0,0,1] neg_hi:[0,0,1]
	v_pk_mul_f32 v[50:51], v[172:173], v[50:51]
	v_pk_fma_f32 v[60:61], v[172:173], v[54:55], v[60:61] neg_lo:[0,0,1] neg_hi:[0,0,1]
	v_pk_fma_f32 v[50:51], v[176:177], v[54:55], v[50:51]
	v_cvt_pk_bf16_f32 v54, v60, v61
	v_cvt_pk_bf16_f32 v55, v58, v59
	v_add_u32_e32 v59, 0x90, v151
	v_pk_mul_f32 v[52:53], v[174:175], v[52:53]
	v_lshlrev_b32_e32 v0, 8, v59
	v_pk_fma_f32 v[52:53], v[178:179], v[56:57], v[52:53]
	v_cvt_pk_bf16_f32 v50, v50, v51
	v_and_b32_e32 v0, 0xfdf00, v0
	v_cvt_pk_bf16_f32 v51, v52, v53
	global_store_dwordx2 v[76:77], v[54:55], off offset:256
	global_store_dwordx2 v[76:77], v[50:51], off offset:384
	v_lshl_add_u64 v[50:51], s[14:15], 0, v[0:1]
	v_lshl_add_u64 v[54:55], s[16:17], 0, v[0:1]
	v_lshl_add_u64 v[50:51], v[50:51], 0, v[146:147]
	v_lshl_add_u64 v[54:55], v[54:55], 0, v[146:147]
	ds_read_b32 v58, v152 offset:576
	v_mad_i64_i32 v[60:61], s[30:31], v59, s75, v[142:143]
	v_lshl_add_u64 v[60:61], v[60:61], 0, v[144:145]
	s_waitcnt lgkmcnt(0)
	v_pk_mul_f32 v[42:43], v[42:43], v[58:59] op_sel_hi:[1,0]
	v_pk_mul_f32 v[46:47], v[46:47], v[58:59] op_sel_hi:[1,0]
	v_pk_mul_f32 v[44:45], v[44:45], v[58:59] op_sel_hi:[1,0]
	v_pk_mul_f32 v[48:49], v[48:49], v[58:59] op_sel_hi:[1,0]
	v_pk_mul_f32 v[36:37], v[36:37], v[58:59] op_sel_hi:[1,0]
	v_pk_mul_f32 v[40:41], v[40:41], v[58:59] op_sel_hi:[1,0]
	v_pk_mul_f32 v[34:35], v[34:35], v[58:59] op_sel_hi:[1,0]
	v_pk_mul_f32 v[38:39], v[38:39], v[58:59] op_sel_hi:[1,0]
	s_waitcnt vmcnt(4)
; __device__ __forceinline__ unsigned cvt_pk_bf16(float lo, float hi) { unsigned r; asm volatile("v_cvt_pk_bf16_f32 %0, %1, %2" : "=v"(r) : "v"(lo), "v"(hi)); return r; }
;     __device__ __forceinline__ void operator()(const f32x4 (&acc)[2][2][4][2], const Unit& u, int wr, int wc, int fr, int fq) const {
;     ...
;             for (int m = 0; m < 4; ++m) { const int rl = wr * 64 + fr + ai * HALF + m * 16, row = u.pm * BM + rl; const float rsc = tab[rl];
;                 const f32x4 c = *(const f32x4*)(cs + (size_t)(row & 4095) * half + d0), s = *(const f32x4*)(sn + (size_t)(row & 4095) * half + d0);
;                 bf16_t* rowp = O + (size_t)row * ldc + gcol;
; #pragma unroll
;                 for (int bj = 0; bj < 2; ++bj) { const f32x4 x1 = acc[ai][bj][m][0] * rsc, x2 = acc[ai][bj][m][1] * rsc;
;                     const f32x4 y1 = x1 * c - x2 * s, y2 = x2 * c + x1 * s;
;                     u32x2 w1, w2; w1.x = cvt_pk_bf16(y1[0], y1[1]); w1.y = cvt_pk_bf16(y1[2], y1[3]); w2.x = cvt_pk_bf16(y2[0], y2[1]); w2.y = cvt_pk_bf16(y2[2], y2[3]);
;                     *(u32x2*)(rowp + bj * HALF) = w1; *(u32x2*)(rowp + bj * HALF + half) = w2; } }
	v_add_u32_e32 v170, 160, v151
	v_lshlrev_b32_e32 v170, 8, v170
	v_and_b32_e32 v170, 0xfff00, v170
	v_mov_b32_e32 v171, 0
	v_lshl_add_u64 v[172:173], s[14:15], 0, v[170:171]
	v_lshl_add_u64 v[176:177], s[16:17], 0, v[170:171]
	v_lshl_add_u64 v[172:173], v[172:173], 0, v[146:147]
	v_lshl_add_u64 v[176:177], v[176:177], 0, v[146:147]
	global_load_dwordx4 v[172:175], v[172:173], off
	global_load_dwordx4 v[176:179], v[176:177], off
	v_pk_mul_f32 v[64:65], v[184:185], v[42:43]
	v_pk_mul_f32 v[42:43], v[180:181], v[42:43]
	v_pk_mul_f32 v[62:63], v[186:187], v[44:45]
	v_pk_mul_f32 v[44:45], v[182:183], v[44:45]
	v_pk_fma_f32 v[42:43], v[184:185], v[46:47], v[42:43]
	v_pk_fma_f32 v[62:63], v[182:183], v[48:49], v[62:63] neg_lo:[0,0,1] neg_hi:[0,0,1]
	v_pk_fma_f32 v[64:65], v[180:181], v[46:47], v[64:65] neg_lo:[0,0,1] neg_hi:[0,0,1]
	v_pk_fma_f32 v[44:45], v[186:187], v[48:49], v[44:45]
	v_cvt_pk_bf16_f32 v46, v64, v65
	v_cvt_pk_bf16_f32 v47, v62, v63
	v_cvt_pk_bf16_f32 v42, v42, v43
	s_nop 0
	v_cvt_pk_bf16_f32 v43, v44, v45
	global_store_dwordx2 v[60:61], v[46:47], off
	global_store_dwordx2 v[60:61], v[42:43], off offset:128
	v_pk_mul_f32 v[42:43], v[186:187], v[36:37]
	v_pk_mul_f32 v[44:45], v[184:185], v[34:35]
	v_pk_fma_f32 v[42:43], v[182:183], v[40:41], v[42:43] neg_lo:[0,0,1] neg_hi:[0,0,1]
	v_pk_mul_f32 v[34:35], v[180:181], v[34:35]
	v_pk_fma_f32 v[44:45], v[180:181], v[38:39], v[44:45] neg_lo:[0,0,1] neg_hi:[0,0,1]
	v_pk_fma_f32 v[34:35], v[184:185], v[38:39], v[34:35]
	v_cvt_pk_bf16_f32 v38, v44, v45
	v_cvt_pk_bf16_f32 v39, v42, v43
	v_add_u32_e32 v43, 0xa0, v151
	v_pk_mul_f32 v[36:37], v[182:183], v[36:37]
	v_lshlrev_b32_e32 v0, 8, v43
	v_pk_fma_f32 v[36:37], v[186:187], v[40:41], v[36:37]
	v_cvt_pk_bf16_f32 v34, v34, v35
	v_and_b32_e32 v0, 0xfef00, v0
	v_cvt_pk_bf16_f32 v35, v36, v37
	global_store_dwordx2 v[60:61], v[38:39], off offset:256
	global_store_dwordx2 v[60:61], v[34:35], off offset:384
	v_lshl_add_u64 v[34:35], s[14:15], 0, v[0:1]
	v_lshl_add_u64 v[38:39], s[16:17], 0, v[0:1]
	v_lshl_add_u64 v[34:35], v[34:35], 0, v[146:147]
	v_lshl_add_u64 v[38:39], v[38:39], 0, v[146:147]
	ds_read_b32 v42, v152 offset:640
	v_mad_i64_i32 v[44:45], s[30:31], v43, s75, v[142:143]
	v_lshl_add_u64 v[44:45], v[44:45], 0, v[144:145]
	s_waitcnt lgkmcnt(0)
	v_pk_mul_f32 v[26:27], v[26:27], v[42:43] op_sel_hi:[1,0]
	v_pk_mul_f32 v[30:31], v[30:31], v[42:43] op_sel_hi:[1,0]
	v_pk_mul_f32 v[28:29], v[28:29], v[42:43] op_sel_hi:[1,0]
	v_pk_mul_f32 v[32:33], v[32:33], v[42:43] op_sel_hi:[1,0]
	v_pk_mul_f32 v[20:21], v[20:21], v[42:43] op_sel_hi:[1,0]
	v_pk_mul_f32 v[24:25], v[24:25], v[42:43] op_sel_hi:[1,0]
	v_pk_mul_f32 v[18:19], v[18:19], v[42:43] op_sel_hi:[1,0]
	v_pk_mul_f32 v[22:23], v[22:23], v[42:43] op_sel_hi:[1,0]
	s_waitcnt vmcnt(4)
	v_add_u32_e32 v170, 176, v151
	v_lshlrev_b32_e32 v170, 8, v170
	v_and_b32_e32 v170, 0xfff00, v170
	v_mov_b32_e32 v171, 0
	v_lshl_add_u64 v[180:181], s[14:15], 0, v[170:171]
	v_lshl_add_u64 v[184:185], s[16:17], 0, v[170:171]
	v_lshl_add_u64 v[180:181], v[180:181], 0, v[146:147]
	v_lshl_add_u64 v[184:185], v[184:185], 0, v[146:147]
	global_load_dwordx4 v[180:183], v[180:181], off
	global_load_dwordx4 v[184:187], v[184:185], off
	v_pk_mul_f32 v[48:49], v[176:177], v[26:27]
	v_pk_mul_f32 v[26:27], v[172:173], v[26:27]
	v_pk_mul_f32 v[46:47], v[178:179], v[28:29]
	v_pk_mul_f32 v[28:29], v[174:175], v[28:29]
	v_pk_fma_f32 v[26:27], v[176:177], v[30:31], v[26:27]
	v_pk_fma_f32 v[46:47], v[174:175], v[32:33], v[46:47] neg_lo:[0,0,1] neg_hi:[0,0,1]
	v_pk_fma_f32 v[48:49], v[172:173], v[30:31], v[48:49] neg_lo:[0,0,1] neg_hi:[0,0,1]
	v_pk_fma_f32 v[28:29], v[178:179], v[32:33], v[28:29]
	v_cvt_pk_bf16_f32 v30, v48, v49
	v_cvt_pk_bf16_f32 v31, v46, v47
	v_cvt_pk_bf16_f32 v26, v26, v27
	s_nop 0
	v_cvt_pk_bf16_f32 v27, v28, v29
	global_store_dwordx2 v[44:45], v[30:31], off
	global_store_dwordx2 v[44:45], v[26:27], off offset:128
	v_pk_mul_f32 v[26:27], v[178:179], v[20:21]
	v_pk_mul_f32 v[28:29], v[176:177], v[18:19]
	v_pk_fma_f32 v[26:27], v[174:175], v[24:25], v[26:27] neg_lo:[0,0,1] neg_hi:[0,0,1]
	v_pk_mul_f32 v[18:19], v[172:173], v[18:19]
	v_pk_fma_f32 v[28:29], v[172:173], v[22:23], v[28:29] neg_lo:[0,0,1] neg_hi:[0,0,1]
	v_pk_fma_f32 v[18:19], v[176:177], v[22:23], v[18:19]
	v_cvt_pk_bf16_f32 v22, v28, v29
	v_cvt_pk_bf16_f32 v23, v26, v27
	v_add_u32_e32 v27, 0xb0, v151
	v_pk_mul_f32 v[20:21], v[174:175], v[20:21]
	v_lshlrev_b32_e32 v0, 8, v27
	v_pk_fma_f32 v[20:21], v[178:179], v[24:25], v[20:21]
	v_cvt_pk_bf16_f32 v18, v18, v19
	v_and_b32_e32 v0, 0xfff00, v0
	v_cvt_pk_bf16_f32 v19, v20, v21
	global_store_dwordx2 v[44:45], v[22:23], off offset:256
	global_store_dwordx2 v[44:45], v[18:19], off offset:384
	v_lshl_add_u64 v[18:19], s[14:15], 0, v[0:1]
	v_lshl_add_u64 v[22:23], s[16:17], 0, v[0:1]
	v_lshl_add_u64 v[18:19], v[18:19], 0, v[146:147]
	v_lshl_add_u64 v[22:23], v[22:23], 0, v[146:147]
	ds_read_b32 v26, v152 offset:704
	v_mad_i64_i32 v[28:29], s[30:31], v27, s75, v[142:143]
	v_lshl_add_u64 v[28:29], v[28:29], 0, v[144:145]
	s_waitcnt lgkmcnt(0)
	v_pk_mul_f32 v[10:11], v[10:11], v[26:27] op_sel_hi:[1,0]
	v_pk_mul_f32 v[14:15], v[14:15], v[26:27] op_sel_hi:[1,0]
	v_pk_mul_f32 v[12:13], v[12:13], v[26:27] op_sel_hi:[1,0]
	v_pk_mul_f32 v[16:17], v[16:17], v[26:27] op_sel_hi:[1,0]
	v_pk_mul_f32 v[4:5], v[4:5], v[26:27] op_sel_hi:[1,0]
	v_pk_mul_f32 v[2:3], v[2:3], v[26:27] op_sel_hi:[1,0]
	v_pk_mul_f32 v[8:9], v[8:9], v[26:27] op_sel_hi:[1,0]
	v_pk_mul_f32 v[6:7], v[6:7], v[26:27] op_sel_hi:[1,0]
	s_mov_b64 s[30:31], -1
	s_waitcnt vmcnt(4)
	v_pk_mul_f32 v[32:33], v[184:185], v[10:11]
	v_pk_mul_f32 v[10:11], v[180:181], v[10:11]
	v_pk_mul_f32 v[30:31], v[186:187], v[12:13]
	v_pk_mul_f32 v[12:13], v[182:183], v[12:13]
	v_pk_fma_f32 v[10:11], v[184:185], v[14:15], v[10:11]
	v_pk_fma_f32 v[30:31], v[182:183], v[16:17], v[30:31] neg_lo:[0,0,1] neg_hi:[0,0,1]
	v_pk_fma_f32 v[32:33], v[180:181], v[14:15], v[32:33] neg_lo:[0,0,1] neg_hi:[0,0,1]
	v_pk_fma_f32 v[12:13], v[186:187], v[16:17], v[12:13]
	v_cvt_pk_bf16_f32 v14, v32, v33
	v_cvt_pk_bf16_f32 v15, v30, v31
	v_cvt_pk_bf16_f32 v10, v10, v11
	s_nop 0
	v_cvt_pk_bf16_f32 v11, v12, v13
	global_store_dwordx2 v[28:29], v[14:15], off
	global_store_dwordx2 v[28:29], v[10:11], off offset:128
	v_pk_mul_f32 v[10:11], v[186:187], v[4:5]
	v_pk_mul_f32 v[12:13], v[184:185], v[2:3]
	v_pk_mul_f32 v[2:3], v[180:181], v[2:3]
	v_pk_fma_f32 v[10:11], v[182:183], v[8:9], v[10:11] neg_lo:[0,0,1] neg_hi:[0,0,1]
	v_pk_fma_f32 v[12:13], v[180:181], v[6:7], v[12:13] neg_lo:[0,0,1] neg_hi:[0,0,1]
	v_pk_mul_f32 v[4:5], v[182:183], v[4:5]
	v_pk_fma_f32 v[2:3], v[184:185], v[6:7], v[2:3]
	v_cvt_pk_bf16_f32 v6, v12, v13
	v_cvt_pk_bf16_f32 v7, v10, v11
	v_pk_fma_f32 v[4:5], v[186:187], v[8:9], v[4:5]
	v_cvt_pk_bf16_f32 v2, v2, v3
	s_nop 0
	v_cvt_pk_bf16_f32 v3, v4, v5
	global_store_dwordx2 v[28:29], v[6:7], off offset:256
	global_store_dwordx2 v[28:29], v[2:3], off offset:384
	s_cbranch_vccnz .LBB0_496
; __device__ __forceinline__ int fresh_lane() { unsigned o_ = ~0u; asm volatile("" : "+s"(o_)); return (int)__builtin_amdgcn_mbcnt_hi(o_, __builtin_amdgcn_mbcnt_lo(o_, 0u)); }
; #define PG8_BAR __builtin_amdgcn_s_barrier()
; template <class Epi, class Sched, bool ALIGN_EPI = false, bool SP2 = false>
; __device__ __forceinline__ void gemm_phase(PG8_LAS unsigned char* lds, const Gemm g, const Sched& S, const Epi& E, const int wid) {
;     ...
;         if constexpr (ALIGN_EPI) { if (wr == 0) PG8_BAR; }
;         if constexpr (!Epi::AFTER_DRAIN) { const int le_ = fresh_lane(); E(acc, cur, wr, wc, le_ & 15, le_ >> 4); S.done(cur); }
;         if (!has_next) break;
; #pragma unroll
;         for (int a = 0; a < 2; ++a)
; #pragma unroll
;             for (int b = 0; b < 2; ++b)
; #pragma unroll
;                 for (int m = 0; m < 4; ++m)
; #pragma unroll
;                     for (int n = 0; n < 2; ++n) acc[a][b][m][n] = (f32x4){zf_, zf_, zf_, zf_};
;         cur = nxt; cA = nA; cB = nB; ++ui;
;         if constexpr (ALIGN_EPI) { if (wr == 1) PG8_BAR; }
;     }
	s_andn2_b64 vcc, exec, s[10:11]
	s_cbranch_vccnz .LBB0_495
	s_barrier
	s_branch .LBB0_495
